# v29 + the second workgroup barrier of the attention work-queue hand-off removed (every item passes at least one barrier before the queue word is written again)
# speedup vs baseline: 1.0094x; 1.0029x over previous
; DI int TIDX() { int t = (int)threadIdx.x; asm volatile("" : "+v"(t)); return t; }
; DI void nsa_attn_item(const Params& p, int b, int g, int qt, bf16_t* smem) {
;   const int lane = TIDX() & 63, wid = TIDX() >> 6, l31 = lane & 31, half = lane >> 5;
;   const int t0 = qt * 64, tw0 = t0 + (wid >> 2) * 32, tq = tw0 + l31, head = g * 4 + (wid & 3); const size_t trow = (size_t)b * S_ + tq;
;   bf16x8 qf[4];
;   const bf16_t* qp = (const bf16_t*)(p.ws + O_NSAQ) + trow * 512 + head * 64;
; #pragma unroll
;   for (int ks = 0; ks < 4; ++ks) qf[ks] = *(const bf16x8*)(qp + ks * 16 + half * 8);
;   {
;     const float* rp = (const float*)(p.ws + O_ROPE8) + trow * 16;
;     u32x4 me = __builtin_bit_cast(u32x4, qf[0]), ot;
; #pragma unroll
;     for (int e = 0; e < 4; ++e) ot[e] = __shfl_xor(me[e], 32);
;     unsigned res[4];
; #pragma unroll
;     for (int e = 0; e < 4; ++e) {
;       float o2[2];
; #pragma unroll
;       for (int u = 0; u < 2; ++u) {
;         const int f = 2 * e + u; const float cs = rp[2 * f], sn = rp[2 * f + 1];
;         const float a = bf2f((bf16_t)(u ? me[e] >> 16 : me[e] & 0xffffu)), o = bf2f((bf16_t)(u ? ot[e] >> 16 : ot[e] & 0xffffu));
;         o2[u] = half == 0 ? a * cs - o * sn : a * cs + o * sn;
;       }
;       res[e] = pk2(o2[0], o2[1]);
;     }
;     qf[0] = __builtin_bit_cast(bf16x8, (u32x4){res[0], res[1], res[2], res[3]});
;   }
;   const float* gts = (const float*)(p.ws + O_GATES) + trow * 24 + head * 3;
;   const int cur = t0 >> 6;
;   f32x16 res[2];
;   {
;     AState st; astate_init(st);
;     const int first = t0 >= 511 ? (t0 - 511) >> 6 : 0, firstw = tw0 >= 511 ? (tw0 - 511) >> 6 : 0;
;     const u64 tmask = lowbits(cur + 1) & ~lowbits(first), wmask = lowbits(cur + 1) & ~lowbits(firstw);
; DI void phase_d(const Params& p, int layer, unsigned char* smem) {
;     ...
;     if (TIDX() == 0) *s_it = (int)atomicAdd(qctr, 1u);
;     __syncthreads();
;     const int it = *s_it;
;     __syncthreads();
;     if (it >= PD_ITEMS) break;
;     const int r = it / 192, w = it % 192, qt = 15 - r;
;     if (w < 64) dense_attn_item<M_MLA>(p, w >> 3, w & 7, qt, (bf16_t*)smem);
;     else if (w < 128) dense_attn_item<M_FOX>(p, (w - 64) >> 3, (w - 64) & 7, qt, (bf16_t*)smem);
;     else { const int i = w - 128, bg = i & 15, q4 = i >> 4; nsa_attn_item(p, bg >> 1, bg & 1, qt * 4 + q4, (bf16_t*)smem); }
.LBB0_594:
	s_or_b64 exec, exec, s[0:1]
	s_waitcnt lgkmcnt(0)
	s_barrier
	ds_read_b32 v0, v174
	s_movk_i32 s0, 0xbff
	s_waitcnt lgkmcnt(0)
	s_nop 0
	v_cmp_lt_i32_e32 vcc, s0, v0
	v_readfirstlane_b32 s2, v0
	s_mov_b64 s[0:1], -1
	s_cbranch_vccnz .LBB0_589
	s_mul_hi_i32 s0, s2, 0xd5555555
	s_lshr_b32 s1, s0, 31
	s_ashr_i32 s73, s0, 5
	s_mul_hi_i32 s0, s2, 0x2aaaaaab
	s_add_i32 s73, s73, s1
	s_lshr_b32 s1, s0, 31
	s_lshr_b32 s0, s0, 5
	s_add_i32 s0, s0, s1
	s_mulk_i32 s0, 0xc0
	s_sub_i32 s72, s2, s0
	s_add_i32 s93, s73, 15
	s_cmp_gt_i32 s72, 63
	s_mov_b64 s[0:1], -1
	s_cbranch_scc0 .LBB0_706
	s_cmpk_gt_u32 s72, 0x7f
	s_cbranch_scc0 .LBB0_664
	s_add_i32 s0, s72, 0xffffff80
	v_mov_b32_e32 v17, v220
	v_mov_b32_e32 v0, v220
	s_lshr_b32 s0, s0, 4
	s_lshl_b32 s1, s93, 2
	s_add_i32 s0, s1, s0
	v_lshrrev_b32_e32 v10, 6, v0
	v_ashrrev_i32_e32 v0, 3, v0
	s_lshl_b32 s16, s0, 6
	v_and_b32_e32 v0, 0xffffffe0, v0
	v_add_u32_e32 v16, s16, v0
	v_and_or_b32 v160, v17, 31, v16
	s_lshl_b32 s1, s72, 11
	s_and_b32 s68, s1, 0x7000
	v_ashrrev_i32_e32 v161, 31, v160
	s_waitcnt vmcnt(9)
	v_lshl_add_u64 v[112:113], v[160:161], 0, s[68:69]
	v_readlane_b32 s4, v240, 26
	s_and_b32 s2, s72, 1
	v_lshlrev_b64 v[2:3], 6, v[112:113]
	v_readlane_b32 s5, v240, 27
	s_lshl_b32 s1, s2, 2
	v_and_or_b32 v122, v10, 3, s1
	v_lshl_add_u64 v[14:15], s[4:5], 0, v[2:3]
	v_readlane_b32 s4, v237, 13
	v_lshlrev_b64 v[22:23], 10, v[112:113]
	v_readlane_b32 s5, v237, 14
	global_load_dwordx4 v[2:5], v[14:15], off offset:16
	global_load_dwordx4 v[6:9], v[14:15], off
	v_bfe_u32 v177, v17, 5, 1
	global_load_dwordx4 v[10:13], v[14:15], off offset:48
	global_load_dwordx4 v[18:21], v[14:15], off offset:32
	v_lshl_add_u64 v[14:15], s[4:5], 0, v[22:23]
	v_lshlrev_b32_e32 v0, 7, v122
	v_lshl_add_u64 v[14:15], v[14:15], 0, v[0:1]
	v_lshlrev_b32_e32 v0, 4, v177
	v_lshl_add_u64 v[14:15], v[14:15], 0, v[0:1]
	global_load_dwordx4 v[22:25], v[14:15], off
	global_load_dwordx4 v[128:131], v[14:15], off offset:32
	global_load_dwordx4 v[132:135], v[14:15], off offset:64
	global_load_dwordx4 v[136:139], v[14:15], off offset:96
	v_cmp_lt_i32_e32 vcc, v222, v223
	v_and_b32_e32 v123, 63, v17
	s_add_i32 s1, s16, 0xfffffe01
	v_cndmask_b32_e32 v0, v221, v222, vcc
	v_lshlrev_b32_e32 v176, 2, v0
	s_ashr_i32 s1, s1, 6
	s_cmp_gt_u32 s0, 7
	s_cselect_b32 s3, s1, 0
	s_add_i32 s1, s0, 1
	s_lshl_b64 s[4:5], -1, s1
	s_not_b64 s[4:5], s[4:5]
	v_cmp_gt_u32_e32 vcc, 32, v123
	s_cmp_lt_u32 s0, 63
	s_cselect_b32 s7, s5, -1
	s_cselect_b32 s6, s4, -1
	s_lshl_b64 s[0:1], -1, s3
	s_cmp_lt_i32 s3, 64
	s_cselect_b32 s1, s1, 0
	s_cselect_b32 s0, s0, 0
	s_and_b32 s20, s72, 15
	s_and_b64 s[0:1], s[0:1], s[6:7]
	s_lshl_b32 s19, s68, 7
	s_lshl_b32 s18, s2, 6
	s_lshl_b32 s17, s20, 18
	s_cmp_eq_u64 s[0:1], 0
	s_waitcnt vmcnt(6)
	v_mov_b32_e32 v15, v8
	v_mov_b32_e32 v8, v7
	v_mov_b32_e32 v7, v4
	v_mov_b32_e32 v4, v3
	s_waitcnt vmcnt(4)
	v_mov_b32_e32 v3, v20
	v_mov_b32_e32 v20, v19
	v_mov_b32_e32 v19, v12
	v_mov_b32_e32 v12, v11
	s_waitcnt vmcnt(3)
	ds_bpermute_b32 v17, v176, v23
	ds_bpermute_b32 v34, v176, v25
	ds_bpermute_b32 v0, v176, v22
	ds_bpermute_b32 v32, v176, v24
	v_mov_b32_e32 v14, v6
	s_waitcnt lgkmcnt(3)
	v_and_b32_e32 v31, 0xffff0000, v17
	v_lshlrev_b32_e32 v30, 16, v17
	s_waitcnt lgkmcnt(2)
	v_and_b32_e32 v35, 0xffff0000, v34
	v_lshlrev_b32_e32 v34, 16, v34
	v_pk_mul_f32 v[4:5], v[4:5], v[30:31]
	v_pk_mul_f32 v[12:13], v[12:13], v[34:35]
	v_mov_b32_e32 v6, v2
	v_mov_b32_e32 v2, v18
	v_mov_b32_e32 v18, v10
	v_lshlrev_b32_e32 v10, 16, v22
	v_and_b32_e32 v11, 0xffff0000, v22
	v_lshlrev_b32_e32 v22, 16, v23
	v_and_b32_e32 v23, 0xffff0000, v23
	v_lshlrev_b32_e32 v26, 16, v24
	v_and_b32_e32 v27, 0xffff0000, v24
	v_lshlrev_b32_e32 v24, 16, v25
	v_and_b32_e32 v25, 0xffff0000, v25
	s_waitcnt lgkmcnt(1)
	v_and_b32_e32 v29, 0xffff0000, v0
	v_lshlrev_b32_e32 v28, 16, v0
	s_waitcnt lgkmcnt(0)
	v_and_b32_e32 v33, 0xffff0000, v32
	v_lshlrev_b32_e32 v32, 16, v32
	v_cndmask_b32_e64 v5, v5, -v5, vcc
	v_cndmask_b32_e64 v4, v4, -v4, vcc
	v_cndmask_b32_e64 v13, v13, -v13, vcc
	v_cndmask_b32_e64 v12, v12, -v12, vcc
	v_pk_mul_f32 v[8:9], v[8:9], v[28:29]
	v_pk_mul_f32 v[20:21], v[20:21], v[32:33]
	v_pk_fma_f32 v[4:5], v[6:7], v[22:23], v[4:5]
	v_pk_fma_f32 v[6:7], v[18:19], v[24:25], v[12:13]
	v_mov_b32_e32 v18, v220
	v_cndmask_b32_e64 v9, v9, -v9, vcc
	v_cndmask_b32_e64 v8, v8, -v8, vcc
	v_cndmask_b32_e64 v21, v21, -v21, vcc
	v_cndmask_b32_e64 v20, v20, -v20, vcc
	v_pk_fma_f32 v[8:9], v[14:15], v[10:11], v[8:9]
	v_and_b32_e32 v17, 31, v18
	v_pk_fma_f32 v[2:3], v[2:3], v[26:27], v[20:21]
	v_sub_u32_e32 v0, v160, v17
	v_cvt_pk_bf16_f32 v140, v8, v9
	v_cvt_pk_bf16_f32 v141, v4, v5
	v_cvt_pk_bf16_f32 v142, v2, v3
	v_cvt_pk_bf16_f32 v143, v6, v7
	v_readfirstlane_b32 s21, v0
	s_cbranch_scc1 .LBB0_625
	s_lshl_b32 s2, s19, 1
	v_readlane_b32 s3, v237, 15
	s_add_u32 s2, s3, s2
	v_readlane_b32 s3, v237, 16
	s_addc_u32 s3, s3, 0
	s_lshl_b32 s4, s18, 1
	s_add_u32 s2, s2, s4
	s_addc_u32 s3, s3, 0
	s_lshl_b32 s4, s17, 1
	v_readlane_b32 s5, v237, 17
	s_add_u32 s10, s5, s4
	v_readlane_b32 s4, v237, 18
	s_addc_u32 s11, s4, 0
	s_add_u32 s4, s0, -1
	s_addc_u32 s5, s1, -1
	s_ff1_i32_b64 s15, s[0:1]
	s_and_b64 s[4:5], s[4:5], s[0:1]
	s_lshl_b32 s68, s15, 7
	s_cmp_eq_u64 s[4:5], 0
	s_cselect_b64 s[8:9], -1, 0
	s_ff1_i32_b64 s12, s[4:5]
	v_min_i32_e32 v0, 0x1ff, v18
	v_ashrrev_i32_e32 v22, 3, v18
	s_and_b64 s[0:1], s[8:9], exec
	v_ashrrev_i32_e32 v124, 3, v0
	v_ashrrev_i32_e32 v23, 31, v22
	s_cselect_b32 s0, s15, s12
	v_lshlrev_b64 v[2:3], 13, v[22:23]
	v_lshlrev_b32_e32 v19, 3, v18
	v_lshl_add_u32 v4, s0, 6, v124
	v_lshlrev_b32_e32 v0, 3, v0
	v_lshl_add_u64 v[14:15], s[10:11], 0, v[2:3]
	v_and_b32_e32 v20, 56, v19
	v_ashrrev_i32_e32 v5, 31, v4
	v_and_b32_e32 v0, 56, v0
	v_lshl_add_u64 v[2:3], v[14:15], 0, s[68:69]
	v_lshlrev_b32_e32 v114, 1, v20
	v_mov_b32_e32 v115, v1
	v_lshlrev_b64 v[4:5], 8, v[4:5]
	v_lshl_add_u64 v[2:3], v[2:3], 0, v[114:115]
	v_lshl_add_u64 v[4:5], s[2:3], 0, v[4:5]
	v_lshlrev_b32_e32 v0, 1, v0
	s_lshl_b32 s68, s0, 7
	v_lshl_add_u64 v[4:5], v[4:5], 0, v[0:1]
	global_load_dwordx4 v[10:13], v[2:3], off
	global_load_dwordx4 v[6:9], v[4:5], off
	v_lshl_add_u64 v[2:3], v[14:15], 0, s[68:69]
	v_lshl_add_u64 v[2:3], v[2:3], 0, v[114:115]
	global_load_dwordx4 v[2:5], v[2:3], off
	v_cmp_gt_i32_e64 s[0:1], s85, v18
	v_mul_lo_u32 v125, v22, s86
	s_and_saveexec_b64 s[10:11], s[0:1]
	s_cbranch_execz .LBB0_600
	s_lshl_b32 s13, s15, 6
	v_add_u32_e32 v22, s13, v124
	v_ashrrev_i32_e32 v23, 31, v22
	v_lshlrev_b64 v[22:23], 8, v[22:23]
	v_lshl_add_u64 v[22:23], s[2:3], 0, v[22:23]
	v_lshl_add_u64 v[22:23], v[22:23], 0, v[0:1]
	global_load_dwordx4 v[22:25], v[22:23], off
	v_lshl_add_u32 v21, v125, 1, v114
	s_waitcnt vmcnt(0)
	ds_write_b128 v21, v[22:25]

; DI int TIDX() { int t = (int)threadIdx.x; asm volatile("" : "+v"(t)); return t; }
; DI void nsa_attn_item(const Params& p, int b, int g, int qt, bf16_t* smem) {
;   const int lane = TIDX() & 63, wid = TIDX() >> 6, l31 = lane & 31, half = lane >> 5;
;   const int t0 = qt * 64, tw0 = t0 + (wid >> 2) * 32, tq = tw0 + l31, head = g * 4 + (wid & 3); const size_t trow = (size_t)b * S_ + tq;
;   bf16x8 qf[4];
;   const bf16_t* qp = (const bf16_t*)(p.ws + O_NSAQ) + trow * 512 + head * 64;
; #pragma unroll
;   for (int ks = 0; ks < 4; ++ks) qf[ks] = *(const bf16x8*)(qp + ks * 16 + half * 8);
;   {
;     const float* rp = (const float*)(p.ws + O_ROPE8) + trow * 16;
;     u32x4 me = __builtin_bit_cast(u32x4, qf[0]), ot;
; #pragma unroll
;     for (int e = 0; e < 4; ++e) ot[e] = __shfl_xor(me[e], 32);
;     unsigned res[4];
; #pragma unroll
;     for (int e = 0; e < 4; ++e) {
;       float o2[2];
; #pragma unroll
;       for (int u = 0; u < 2; ++u) {
;         const int f = 2 * e + u; const float cs = rp[2 * f], sn = rp[2 * f + 1];
;         const float a = bf2f((bf16_t)(u ? me[e] >> 16 : me[e] & 0xffffu)), o = bf2f((bf16_t)(u ? ot[e] >> 16 : ot[e] & 0xffffu));
;         o2[u] = half == 0 ? a * cs - o * sn : a * cs + o * sn;
;       }
;       res[e] = pk2(o2[0], o2[1]);
;     }
;     qf[0] = __builtin_bit_cast(bf16x8, (u32x4){res[0], res[1], res[2], res[3]});
;   }
;   const float* gts = (const float*)(p.ws + O_GATES) + trow * 24 + head * 3;
;   const int cur = t0 >> 6;
;   f32x16 res[2];
;   {
;     AState st; astate_init(st);
;     const int first = t0 >= 511 ? (t0 - 511) >> 6 : 0, firstw = tw0 >= 511 ? (tw0 - 511) >> 6 : 0;
;     const u64 tmask = lowbits(cur + 1) & ~lowbits(first), wmask = lowbits(cur + 1) & ~lowbits(firstw);
; DI void phase_d(const Params& p, int layer, unsigned char* smem) {
;     ...
;     if (TIDX() == 0) *s_it = (int)atomicAdd(qctr, 1u);
;     __syncthreads();
;     const int it = *s_it;
;     __syncthreads();
;     if (it >= PD_ITEMS) break;
;     const int r = it / 192, w = it % 192, qt = 15 - r;
;     if (w < 64) dense_attn_item<M_MLA>(p, w >> 3, w & 7, qt, (bf16_t*)smem);
;     else if (w < 128) dense_attn_item<M_FOX>(p, (w - 64) >> 3, (w - 64) & 7, qt, (bf16_t*)smem);
;     else { const int i = w - 128, bg = i & 15, q4 = i >> 4; nsa_attn_item(p, bg >> 1, bg & 1, qt * 4 + q4, (bf16_t*)smem); }
.LBB0_1628:
	s_or_b64 exec, exec, s[0:1]
	s_waitcnt lgkmcnt(0)
	s_barrier
	ds_read_b32 v0, v174
	s_movk_i32 s0, 0xbff
	s_waitcnt lgkmcnt(0)
	s_nop 0
	v_cmp_lt_i32_e32 vcc, s0, v0
	v_readfirstlane_b32 s2, v0
	s_mov_b64 s[0:1], -1
	s_cbranch_vccnz .LBB0_1623
	s_mul_hi_i32 s0, s2, 0xd5555555
	s_lshr_b32 s1, s0, 31
	s_ashr_i32 s73, s0, 5
	s_mul_hi_i32 s0, s2, 0x2aaaaaab
	s_add_i32 s73, s73, s1
	s_lshr_b32 s1, s0, 31
	s_lshr_b32 s0, s0, 5
	s_add_i32 s0, s0, s1
	s_mulk_i32 s0, 0xc0
	s_sub_i32 s72, s2, s0
	s_add_i32 s93, s73, 15
	s_cmp_gt_i32 s72, 63
	s_mov_b64 s[0:1], -1
	s_cbranch_scc0 .LBB0_1740
	s_cmpk_gt_u32 s72, 0x7f
	s_cbranch_scc0 .LBB0_1698
	s_add_i32 s0, s72, 0xffffff80
	s_waitcnt vmcnt(9)
	v_mov_b32_e32 v17, v220
	v_mov_b32_e32 v0, v220
	s_lshr_b32 s0, s0, 4
	s_lshl_b32 s1, s93, 2
	s_add_i32 s0, s1, s0
	v_lshrrev_b32_e32 v10, 6, v0
	v_ashrrev_i32_e32 v0, 3, v0
	s_lshl_b32 s16, s0, 6
	v_and_b32_e32 v0, 0xffffffe0, v0
	v_add_u32_e32 v16, s16, v0
	v_and_or_b32 v160, v17, 31, v16
	s_lshl_b32 s1, s72, 11
	s_and_b32 s68, s1, 0x7000
	v_ashrrev_i32_e32 v161, 31, v160
	v_lshl_add_u64 v[112:113], v[160:161], 0, s[68:69]
	v_readlane_b32 s4, v240, 26
	s_and_b32 s2, s72, 1
	v_lshlrev_b64 v[2:3], 6, v[112:113]
	v_readlane_b32 s5, v240, 27
	s_lshl_b32 s1, s2, 2
	v_and_or_b32 v122, v10, 3, s1
	v_lshl_add_u64 v[14:15], s[4:5], 0, v[2:3]
	v_readlane_b32 s4, v237, 13
	s_waitcnt vmcnt(8)
	v_lshlrev_b64 v[22:23], 10, v[112:113]
	v_readlane_b32 s5, v237, 14
	global_load_dwordx4 v[2:5], v[14:15], off offset:16
	global_load_dwordx4 v[6:9], v[14:15], off
	v_bfe_u32 v177, v17, 5, 1
	global_load_dwordx4 v[10:13], v[14:15], off offset:48
	global_load_dwordx4 v[18:21], v[14:15], off offset:32
	v_lshl_add_u64 v[14:15], s[4:5], 0, v[22:23]
	v_lshlrev_b32_e32 v0, 7, v122
	v_lshl_add_u64 v[14:15], v[14:15], 0, v[0:1]
	v_lshlrev_b32_e32 v0, 4, v177
	v_lshl_add_u64 v[14:15], v[14:15], 0, v[0:1]
	global_load_dwordx4 v[22:25], v[14:15], off
	global_load_dwordx4 v[128:131], v[14:15], off offset:32
	global_load_dwordx4 v[132:135], v[14:15], off offset:64
	global_load_dwordx4 v[136:139], v[14:15], off offset:96
	v_cmp_lt_i32_e32 vcc, v222, v223
	v_and_b32_e32 v123, 63, v17
	s_add_i32 s1, s16, 0xfffffe01
	v_cndmask_b32_e32 v0, v221, v222, vcc
	v_lshlrev_b32_e32 v176, 2, v0
	s_ashr_i32 s1, s1, 6
	s_cmp_gt_u32 s0, 7
	s_cselect_b32 s3, s1, 0
	s_add_i32 s1, s0, 1
	s_lshl_b64 s[4:5], -1, s1
	s_not_b64 s[4:5], s[4:5]
	v_cmp_gt_u32_e32 vcc, 32, v123
	s_cmp_lt_u32 s0, 63
	s_cselect_b32 s7, s5, -1
	s_cselect_b32 s6, s4, -1
	s_lshl_b64 s[0:1], -1, s3
	s_cmp_lt_i32 s3, 64
	s_cselect_b32 s1, s1, 0
	s_cselect_b32 s0, s0, 0
	s_and_b32 s20, s72, 15
	s_and_b64 s[0:1], s[0:1], s[6:7]
	s_lshl_b32 s19, s68, 7
	s_lshl_b32 s18, s2, 6
	s_lshl_b32 s17, s20, 18
	s_cmp_eq_u64 s[0:1], 0
	s_waitcnt vmcnt(6)
	v_mov_b32_e32 v15, v8
	v_mov_b32_e32 v8, v7
	v_mov_b32_e32 v7, v4
	v_mov_b32_e32 v4, v3
	s_waitcnt vmcnt(4)
	v_mov_b32_e32 v3, v20
	v_mov_b32_e32 v20, v19
	v_mov_b32_e32 v19, v12
	v_mov_b32_e32 v12, v11
	s_waitcnt vmcnt(3)
	ds_bpermute_b32 v17, v176, v23
	ds_bpermute_b32 v34, v176, v25
	ds_bpermute_b32 v0, v176, v22
	ds_bpermute_b32 v32, v176, v24
	v_mov_b32_e32 v14, v6
	s_waitcnt lgkmcnt(3)
	v_and_b32_e32 v31, 0xffff0000, v17
	v_lshlrev_b32_e32 v30, 16, v17
	s_waitcnt lgkmcnt(2)
	v_and_b32_e32 v35, 0xffff0000, v34
	v_lshlrev_b32_e32 v34, 16, v34
	v_pk_mul_f32 v[4:5], v[4:5], v[30:31]
	v_pk_mul_f32 v[12:13], v[12:13], v[34:35]
	v_mov_b32_e32 v6, v2
	v_mov_b32_e32 v2, v18
	v_mov_b32_e32 v18, v10
	v_lshlrev_b32_e32 v10, 16, v22
	v_and_b32_e32 v11, 0xffff0000, v22
	v_lshlrev_b32_e32 v22, 16, v23
	v_and_b32_e32 v23, 0xffff0000, v23
	v_lshlrev_b32_e32 v26, 16, v24
	v_and_b32_e32 v27, 0xffff0000, v24
	v_lshlrev_b32_e32 v24, 16, v25
	v_and_b32_e32 v25, 0xffff0000, v25
	s_waitcnt lgkmcnt(1)
	v_and_b32_e32 v29, 0xffff0000, v0
	v_lshlrev_b32_e32 v28, 16, v0
	s_waitcnt lgkmcnt(0)
	v_and_b32_e32 v33, 0xffff0000, v32
	v_lshlrev_b32_e32 v32, 16, v32
	v_cndmask_b32_e64 v5, v5, -v5, vcc
	v_cndmask_b32_e64 v4, v4, -v4, vcc
	v_cndmask_b32_e64 v13, v13, -v13, vcc
	v_cndmask_b32_e64 v12, v12, -v12, vcc
	v_pk_mul_f32 v[8:9], v[8:9], v[28:29]
	v_pk_mul_f32 v[20:21], v[20:21], v[32:33]
	v_pk_fma_f32 v[4:5], v[6:7], v[22:23], v[4:5]
	v_pk_fma_f32 v[6:7], v[18:19], v[24:25], v[12:13]
	v_mov_b32_e32 v18, v220
	v_cndmask_b32_e64 v9, v9, -v9, vcc
	v_cndmask_b32_e64 v8, v8, -v8, vcc
	v_cndmask_b32_e64 v21, v21, -v21, vcc
	v_cndmask_b32_e64 v20, v20, -v20, vcc
	v_pk_fma_f32 v[8:9], v[14:15], v[10:11], v[8:9]
	v_and_b32_e32 v17, 31, v18
	v_pk_fma_f32 v[2:3], v[2:3], v[26:27], v[20:21]
	v_sub_u32_e32 v0, v160, v17
	v_cvt_pk_bf16_f32 v140, v8, v9
	v_cvt_pk_bf16_f32 v141, v4, v5
	v_cvt_pk_bf16_f32 v142, v2, v3
	v_cvt_pk_bf16_f32 v143, v6, v7
	v_readfirstlane_b32 s21, v0
	s_cbranch_scc1 .LBB0_1659
	s_lshl_b32 s2, s19, 1
	v_readlane_b32 s3, v237, 15
	s_add_u32 s2, s3, s2
	v_readlane_b32 s3, v237, 16
	s_addc_u32 s3, s3, 0
	s_lshl_b32 s4, s18, 1
	s_add_u32 s2, s2, s4
	s_addc_u32 s3, s3, 0
	s_lshl_b32 s4, s17, 1
	v_readlane_b32 s5, v237, 17
	s_add_u32 s10, s5, s4
	v_readlane_b32 s4, v237, 18
	s_addc_u32 s11, s4, 0
	s_add_u32 s4, s0, -1
	s_addc_u32 s5, s1, -1
	s_ff1_i32_b64 s15, s[0:1]
	s_and_b64 s[4:5], s[4:5], s[0:1]
	s_lshl_b32 s68, s15, 7
	s_cmp_eq_u64 s[4:5], 0
	s_cselect_b64 s[8:9], -1, 0
	s_ff1_i32_b64 s12, s[4:5]
	v_min_i32_e32 v0, 0x1ff, v18
	v_ashrrev_i32_e32 v22, 3, v18
	s_and_b64 s[0:1], s[8:9], exec
	v_ashrrev_i32_e32 v124, 3, v0
	v_ashrrev_i32_e32 v23, 31, v22
	s_cselect_b32 s0, s15, s12
	v_lshlrev_b64 v[2:3], 13, v[22:23]
	v_lshlrev_b32_e32 v19, 3, v18
	v_lshl_add_u32 v4, s0, 6, v124
	v_lshlrev_b32_e32 v0, 3, v0
	v_lshl_add_u64 v[14:15], s[10:11], 0, v[2:3]
	v_and_b32_e32 v20, 56, v19
	v_ashrrev_i32_e32 v5, 31, v4
	v_and_b32_e32 v0, 56, v0
	v_lshl_add_u64 v[2:3], v[14:15], 0, s[68:69]
	v_lshlrev_b32_e32 v114, 1, v20
	v_mov_b32_e32 v115, v1
	v_lshlrev_b64 v[4:5], 8, v[4:5]
	v_lshl_add_u64 v[2:3], v[2:3], 0, v[114:115]
	v_lshl_add_u64 v[4:5], s[2:3], 0, v[4:5]
	v_lshlrev_b32_e32 v0, 1, v0
	s_lshl_b32 s68, s0, 7
	v_lshl_add_u64 v[4:5], v[4:5], 0, v[0:1]
	global_load_dwordx4 v[10:13], v[2:3], off
	global_load_dwordx4 v[6:9], v[4:5], off
	v_lshl_add_u64 v[2:3], v[14:15], 0, s[68:69]
	v_lshl_add_u64 v[2:3], v[2:3], 0, v[114:115]
	global_load_dwordx4 v[2:5], v[2:3], off
	v_cmp_gt_i32_e64 s[0:1], s85, v18
	v_mul_lo_u32 v125, v22, s86
	s_and_saveexec_b64 s[10:11], s[0:1]
	s_cbranch_execz .LBB0_1634
	s_lshl_b32 s13, s15, 6
	v_add_u32_e32 v22, s13, v124
	v_ashrrev_i32_e32 v23, 31, v22
	v_lshlrev_b64 v[22:23], 8, v[22:23]
	v_lshl_add_u64 v[22:23], s[2:3], 0, v[22:23]
	v_lshl_add_u64 v[22:23], v[22:23], 0, v[0:1]
	global_load_dwordx4 v[22:25], v[22:23], off
	v_lshl_add_u32 v21, v125, 1, v114
	s_waitcnt vmcnt(0)
	ds_write_b128 v21, v[22:25]
